# sample attention: running-max subtraction folded into the QK MFMA accumulator init (exp2 directly on MFMA output; correction only on the rare rescale path)
# speedup vs baseline: 1.0069x; 1.0069x over previous
.LBB0_374:
	s_andn2_saveexec_b64 s[0:1], s[0:1]
	v_lshlrev_b64 v[0:1], 10, v[2:3]
	v_lshl_add_u64 v[0:1], s[2:3], 0, v[0:1]
	v_mov_b32_e32 v13, v137
	v_lshl_add_u64 v[0:1], v[0:1], 0, v[12:13]
	s_or_b64 exec, exec, s[0:1]
	s_ashr_i32 s71, s70, 31
	s_lshl_b64 s[0:1], s[70:71], 1
	v_readlane_b32 s4, v252, 63
	v_readlane_b32 s5, v253, 0
	s_add_u32 s0, s4, s0
	s_addc_u32 s1, s5, s1
	v_mov_b32_e32 v15, v137
	global_load_dwordx4 v[104:107], v[0:1], off
	v_lshl_add_u64 v[0:1], s[0:1], 0, v[14:15]
	v_lshl_add_u64 v[2:3], v[0:1], 0, v[136:137]
	v_mov_b32_e32 v121, v137
	v_lshl_add_u64 v[0:1], v[0:1], 0, v[120:121]
	global_load_dwordx4 v[108:111], v[2:3], off
	global_load_dwordx4 v[112:115], v[0:1], off
	v_lshl_add_u64 v[122:123], s[4:5], 0, v[14:15]
	v_readlane_b32 s4, v253, 3
	s_add_i32 s0, s22, 0x2080
	v_mov_b32_e32 v9, v137
	v_readlane_b32 s5, v253, 4
	v_mov_b32_e32 v11, v137
	v_mov_b32_e32 v13, v137
	v_mov_b32_e32 v14, v137
	v_lshlrev_b32_e32 v118, 3, v19
	v_mul_u32_u24_e32 v152, 0x90, v16
	v_mul_u32_u24_e32 v153, 0x90, v17
	v_lshl_add_u32 v154, v19, 4, s24
	v_lshl_add_u64 v[124:125], s[4:5], 0, v[8:9]
	v_lshl_add_u64 v[126:127], s[2:3], 0, v[8:9]
	v_lshl_add_u64 v[128:129], s[4:5], 0, v[10:11]
	v_lshl_add_u64 v[130:131], s[2:3], 0, v[10:11]
	v_lshl_add_u64 v[132:133], s[4:5], 0, v[12:13]
	v_lshl_add_u64 v[134:135], s[2:3], 0, v[12:13]
	v_mul_u32_u24_e32 v155, 0xd0, v18
	v_mul_u32_u24_e32 v142, 0x90, v18
	v_add_u32_sdwa v156, s0, v22 dst_sel:DWORD dst_unused:UNUSED_PAD src0_sel:DWORD src1_sel:WORD_1
	v_add_u32_sdwa v157, s0, v21 dst_sel:DWORD dst_unused:UNUSED_PAD src0_sel:DWORD src1_sel:WORD_1
	v_add_u32_e32 v158, s0, v20
	v_mov_b32_e32 v0, v137
	v_mov_b32_e32 v1, v137
	v_mov_b32_e32 v2, v137
	v_mov_b32_e32 v3, v137
	v_mov_b32_e32 v4, v137
	v_mov_b32_e32 v5, v137
	v_mov_b32_e32 v6, v137
	v_mov_b32_e32 v7, v137
	v_mov_b32_e32 v8, v137
	v_mov_b32_e32 v10, v137
	v_mov_b32_e32 v12, v137
	v_mov_b64_e32 v[30:31], v[14:15]
	v_add_u32_e32 v143, s24, v118
	s_mov_b32 s1, 0
	v_mov_b32_e32 v151, 0xf149f2ca
	v_mov_b32_e32 v119, 0
	v_mov_b64_e32 v[28:29], v[12:13]
	v_mov_b64_e32 v[26:27], v[10:11]
	v_mov_b64_e32 v[24:25], v[8:9]
	v_mov_b64_e32 v[22:23], v[6:7]
	v_mov_b64_e32 v[20:21], v[4:5]
	v_mov_b64_e32 v[18:19], v[2:3]
	v_mov_b64_e32 v[16:17], v[0:1]
	s_mov_b32 s3, 0
	s_movk_i32 s4, 0xff80
	s_mov_b32 s5, -1
	v_mov_b32_e32 v238, 0x1000
	v_mov_b32_e32 v239, 0x10000
	v_add_u32_e32 v32, s1, v158
	v_ashrrev_i32_e32 v33, 31, v32
	v_lshlrev_b64 v[34:35], 10, v[32:33]
	v_lshlrev_b64 v[32:33], 6, v[32:33]
	v_lshl_add_u64 v[32:33], v[124:125], 0, v[32:33]
	v_lshl_add_u64 v[34:35], v[126:127], 0, v[34:35]
	v_lshl_add_u64 v[32:33], v[32:33], 0, s[4:5]
	v_cndmask_b32_e64 v241, v33, v35, s[40:41]
	v_cndmask_b32_e64 v240, v32, v34, s[40:41]
	v_add_u32_e32 v32, s1, v157
	v_ashrrev_i32_e32 v33, 31, v32
	v_lshlrev_b64 v[34:35], 10, v[32:33]
	v_lshlrev_b64 v[32:33], 6, v[32:33]
	v_lshl_add_u64 v[32:33], v[128:129], 0, v[32:33]
	v_lshl_add_u64 v[34:35], v[130:131], 0, v[34:35]
	v_lshl_add_u64 v[32:33], v[32:33], 0, s[4:5]
	v_cndmask_b32_e64 v243, v33, v35, s[42:43]
	v_cndmask_b32_e64 v242, v32, v34, s[42:43]
	v_add_u32_e32 v32, s1, v156
	v_ashrrev_i32_e32 v33, 31, v32
	v_lshlrev_b64 v[34:35], 10, v[32:33]
	v_lshlrev_b64 v[32:33], 6, v[32:33]
	v_lshl_add_u64 v[32:33], v[132:133], 0, v[32:33]
	v_lshl_add_u64 v[34:35], v[134:135], 0, v[34:35]
	v_lshl_add_u64 v[32:33], v[32:33], 0, s[4:5]
	v_cndmask_b32_e64 v245, v33, v35, s[44:45]
	v_cndmask_b32_e64 v244, v32, v34, s[44:45]
	s_add_i32 s22, s0, s1
	s_ashr_i32 s23, s22, 31
	v_lshl_add_u64 v[32:33], s[22:23], 1, v[122:123]
	v_lshl_add_u64 v[246:247], v[32:33], 0, v[136:137]
	v_mov_b32_e32 v121, v137
	v_lshl_add_u64 v[248:249], v[32:33], 0, v[120:121]
	v_mov_b32_e32 v120, 0
	v_mov_b32_e32 v121, 0
	v_mov_b32_e32 v122, 0
	v_mov_b32_e32 v123, 0
	v_mov_b32_e32 v124, 0
	v_mov_b32_e32 v125, 0
	v_mov_b32_e32 v126, 0
	v_mov_b32_e32 v127, 0
	v_mov_b32_e32 v128, 0
	v_mov_b32_e32 v129, 0
	v_mov_b32_e32 v130, 0
	v_mov_b32_e32 v131, 0
	v_mov_b32_e32 v132, 0
	v_mov_b32_e32 v133, 0
	v_mov_b32_e32 v134, 0
	v_mov_b32_e32 v135, 0
	s_waitcnt lgkmcnt(0)
	s_barrier
	v_readfirstlane_b32 s22, v139
	s_bitcmp1_b32 s22, 8
	s_cbranch_scc0 .Lsa_no_e1
	s_barrier

.Lsa_noq:
	v_add3_u32 v160, s22, v144, v145
	v_add3_u32 v161, s22, v146, v147
	s_setprio 1
	s_waitcnt lgkmcnt(0)
	v_mfma_f32_32x32x16_bf16 v[32:47], v[190:193], v[84:87], v[120:135]
	v_mfma_f32_32x32x16_bf16 v[48:63], v[214:217], v[84:87], v[120:135]
	s_waitcnt vmcnt(4)
	ds_write_b128 v160, v[96:99]
	v_add3_u32 v160, s22, v148, v149
	v_mfma_f32_32x32x16_bf16 v[32:47], v[194:197], v[80:83], v[32:47]
	v_mfma_f32_32x32x16_bf16 v[48:63], v[218:221], v[80:83], v[48:63]
	s_waitcnt vmcnt(3)
	ds_write_b128 v161, v[100:103]
	v_add_u32_e32 v161, s23, v150
	v_mfma_f32_32x32x16_bf16 v[32:47], v[198:201], v[76:79], v[32:47]
	v_mfma_f32_32x32x16_bf16 v[48:63], v[222:225], v[76:79], v[48:63]
	s_waitcnt vmcnt(2)
	ds_write_b128 v160, v[104:107]
	v_add_u32_e32 v160, v161, v152
	v_add_u32_e32 v161, v161, v153
	v_mfma_f32_32x32x16_bf16 v[32:47], v[202:205], v[72:75], v[32:47]
	v_mfma_f32_32x32x16_bf16 v[48:63], v[226:229], v[72:75], v[48:63]
	s_waitcnt vmcnt(1)
	ds_write_b128 v160, v[108:111] offset:26624
	s_waitcnt vmcnt(0)
	ds_write_b128 v161, v[112:115] offset:26624
	v_cndmask_b32_e64 v160, v238, v239, s[40:41]
	v_cndmask_b32_e64 v161, v238, v239, s[42:43]
	v_mfma_f32_32x32x16_bf16 v[32:47], v[206:209], v[68:71], v[32:47]
	v_mfma_f32_32x32x16_bf16 v[48:63], v[230:233], v[68:71], v[48:63]
	s_cmpk_gt_u32 s2, 0x46
	s_cbranch_scc1 .Lsa_nold
	global_load_dwordx4 v[96:99], v[240:241], off
	global_load_dwordx4 v[100:103], v[242:243], off
	global_load_dwordx4 v[104:107], v[244:245], off
	global_load_dwordx4 v[108:111], v[246:247], off
	global_load_dwordx4 v[112:115], v[248:249], off
.Lsa_nold:
	v_add_co_u32_e32 v240, vcc, v240, v160
	v_addc_co_u32_e32 v241, vcc, 0, v241, vcc
	v_add_co_u32_e32 v242, vcc, v242, v161
	v_addc_co_u32_e32 v243, vcc, 0, v243, vcc
	v_cndmask_b32_e64 v160, v238, v239, s[44:45]
	v_mfma_f32_32x32x16_bf16 v[32:47], v[210:213], v[64:67], v[32:47]
	v_mfma_f32_32x32x16_bf16 v[48:63], v[234:237], v[64:67], v[48:63]
	v_add_co_u32_e32 v244, vcc, v244, v160
	v_addc_co_u32_e32 v245, vcc, 0, v245, vcc
	v_add_co_u32_e32 v246, vcc, 0x80, v246
	v_addc_co_u32_e32 v247, vcc, 0, v247, vcc
	v_add_co_u32_e32 v248, vcc, 0x80, v248
	v_addc_co_u32_e32 v249, vcc, 0, v249, vcc
	s_setprio 0
	s_nop 10
	v_max_f32_e32 v136, v48, v48
	v_max_f32_e32 v159, v32, v32
	v_max_f32_e32 v136, v159, v136
	v_max3_f32 v136, v136, v33, v49
	v_max3_f32 v136, v136, v34, v50
	v_max3_f32 v136, v136, v35, v51
	v_max3_f32 v136, v136, v36, v52
	v_max3_f32 v136, v136, v37, v53
	v_max3_f32 v136, v136, v38, v54
	v_max3_f32 v136, v136, v39, v55
	v_max3_f32 v136, v136, v40, v56
	v_max3_f32 v136, v136, v41, v57
	v_max3_f32 v136, v136, v42, v58
	v_max3_f32 v136, v136, v43, v59
	v_max3_f32 v136, v136, v44, v60
	v_max3_f32 v136, v136, v45, v61
	v_max3_f32 v136, v136, v46, v62
	v_max3_f32 v159, v136, v47, v63
	v_mov_b32_e32 v160, v159
	s_nop 1
	v_permlane32_swap_b32 v160, v159
	v_max_f32_e32 v159, v159, v160
	v_add_f32_e32 v160, v151, v120
	v_add_f32_e32 v160, 0x41000000, v160
	v_cmp_gt_f32_e32 vcc, v159, v160
	s_cbranch_vccz .LBB0_381
	v_sub_f32_e32 v159, v159, v120
	v_max_f32_e32 v159, v159, v159
	v_max_f32_e32 v160, v151, v151
	v_max_f32_e32 v159, v160, v159
	v_sub_f32_e32 v151, v151, v159
	v_exp_f32_e32 v160, v151
	v_mov_b32_e32 v151, v159
	v_add_f32_e32 v162, v120, v151
	v_pk_mul_f32 v[30:31], v[30:31], v[160:161] op_sel_hi:[1,0]
	v_pk_mul_f32 v[28:29], v[28:29], v[160:161] op_sel_hi:[1,0]
	v_pk_mul_f32 v[26:27], v[26:27], v[160:161] op_sel_hi:[1,0]
	v_pk_mul_f32 v[24:25], v[24:25], v[160:161] op_sel_hi:[1,0]
	v_pk_mul_f32 v[22:23], v[22:23], v[160:161] op_sel_hi:[1,0]
	v_pk_mul_f32 v[20:21], v[20:21], v[160:161] op_sel_hi:[1,0]
	v_pk_mul_f32 v[18:19], v[18:19], v[160:161] op_sel_hi:[1,0]
	v_pk_mul_f32 v[16:17], v[16:17], v[160:161] op_sel_hi:[1,0]
	v_pk_mul_f32 v[14:15], v[14:15], v[160:161] op_sel_hi:[1,0]
	v_pk_mul_f32 v[12:13], v[12:13], v[160:161] op_sel_hi:[1,0]
	v_pk_mul_f32 v[10:11], v[10:11], v[160:161] op_sel_hi:[1,0]
	v_pk_mul_f32 v[8:9], v[8:9], v[160:161] op_sel_hi:[1,0]
	v_pk_mul_f32 v[6:7], v[6:7], v[160:161] op_sel_hi:[1,0]
	v_pk_mul_f32 v[4:5], v[4:5], v[160:161] op_sel_hi:[1,0]
	v_pk_mul_f32 v[2:3], v[2:3], v[160:161] op_sel_hi:[1,0]
	v_pk_mul_f32 v[0:1], v[0:1], v[160:161] op_sel_hi:[1,0]
	v_mul_f32_e32 v119, v119, v160
	v_sub_f32_e32 v32, v32, v162
	v_sub_f32_e32 v33, v33, v162
	v_sub_f32_e32 v34, v34, v162
	v_sub_f32_e32 v35, v35, v162
	v_sub_f32_e32 v36, v36, v162
	v_sub_f32_e32 v37, v37, v162
	v_sub_f32_e32 v38, v38, v162
	v_sub_f32_e32 v39, v39, v162
	v_sub_f32_e32 v40, v40, v162
	v_sub_f32_e32 v41, v41, v162
	v_sub_f32_e32 v42, v42, v162
	v_sub_f32_e32 v43, v43, v162
	v_sub_f32_e32 v44, v44, v162
	v_sub_f32_e32 v45, v45, v162
	v_sub_f32_e32 v46, v46, v162
	v_sub_f32_e32 v47, v47, v162
	v_sub_f32_e32 v48, v48, v162
	v_sub_f32_e32 v49, v49, v162
	v_sub_f32_e32 v50, v50, v162
	v_sub_f32_e32 v51, v51, v162
	v_sub_f32_e32 v52, v52, v162
	v_sub_f32_e32 v53, v53, v162
	v_sub_f32_e32 v54, v54, v162
	v_sub_f32_e32 v55, v55, v162
	v_sub_f32_e32 v56, v56, v162
	v_sub_f32_e32 v57, v57, v162
	v_sub_f32_e32 v58, v58, v162
	v_sub_f32_e32 v59, v59, v162
	v_sub_f32_e32 v60, v60, v162
	v_sub_f32_e32 v61, v61, v162
	v_sub_f32_e32 v62, v62, v162
	v_sub_f32_e32 v63, v63, v162
	v_xor_b32_e32 v120, 0x80000000, v151
	v_mov_b32_e32 v121, v120
	v_mov_b32_e32 v122, v120
	v_mov_b32_e32 v123, v120
	v_mov_b32_e32 v124, v120
	v_mov_b32_e32 v125, v120
	v_mov_b32_e32 v126, v120
	v_mov_b32_e32 v127, v120
	v_mov_b32_e32 v128, v120
	v_mov_b32_e32 v129, v120
	v_mov_b32_e32 v130, v120
	v_mov_b32_e32 v131, v120
	v_mov_b32_e32 v132, v120
	v_mov_b32_e32 v133, v120
	v_mov_b32_e32 v134, v120
	v_mov_b32_e32 v135, v120
.LBB0_381:
	s_barrier
	s_mulk_i32 s3, 0x2400
	v_add3_u32 v190, v143, s3, v142
	v_add_u32_e32 v191, 0x6800, v190
	v_add_u32_e32 v192, 0x7a00, v190
	ds_read2_b64 v[194:197], v191 offset1:2
	ds_read2_b64 v[198:201], v192 offset1:2
	ds_read2_b64 v[202:205], v191 offset0:4 offset1:6
	ds_read2_b64 v[206:209], v192 offset0:4 offset1:6
	ds_read2_b64 v[210:213], v191 offset0:8 offset1:10
	ds_read2_b64 v[214:217], v192 offset0:8 offset1:10
	ds_read2_b64 v[218:221], v191 offset0:12 offset1:14
	ds_read2_b64 v[222:225], v192 offset0:12 offset1:14
	v_exp_f32_e32 v32, v32
	v_exp_f32_e32 v33, v33
	v_exp_f32_e32 v34, v34
	v_exp_f32_e32 v35, v35
	v_exp_f32_e32 v36, v36
	v_exp_f32_e32 v37, v37
	v_exp_f32_e32 v38, v38
	v_exp_f32_e32 v39, v39
	v_cvt_pk_bf16_f32 v160, v32, v33
	v_cvt_pk_bf16_f32 v161, v34, v35
	v_cvt_pk_bf16_f32 v162, v36, v37
	v_cvt_pk_bf16_f32 v163, v38, v39
	v_add_f32_e32 v168, v32, v33
	v_add_f32_e32 v169, v34, v35
	v_add_f32_e32 v168, v168, v36
	v_add_f32_e32 v169, v169, v37
	v_add_f32_e32 v168, v168, v38
	v_add_f32_e32 v169, v169, v39
	s_waitcnt lgkmcnt(6)
	v_mfma_f32_32x32x16_bf16 v[16:31], v[194:197], v[160:163], v[16:31]
	v_mfma_f32_32x32x16_bf16 v[0:15], v[198:201], v[160:163], v[0:15]
	v_exp_f32_e32 v40, v40
	v_exp_f32_e32 v41, v41
	v_exp_f32_e32 v42, v42
	v_exp_f32_e32 v43, v43
	v_exp_f32_e32 v44, v44
	v_exp_f32_e32 v45, v45
	v_exp_f32_e32 v46, v46
	v_exp_f32_e32 v47, v47
	v_cvt_pk_bf16_f32 v164, v40, v41
	v_cvt_pk_bf16_f32 v165, v42, v43
	v_cvt_pk_bf16_f32 v166, v44, v45
	v_cvt_pk_bf16_f32 v167, v46, v47
	v_add_f32_e32 v168, v168, v40
	v_add_f32_e32 v169, v169, v41
	v_add_f32_e32 v168, v168, v42
	v_add_f32_e32 v169, v169, v43
	v_add_f32_e32 v168, v168, v44
	v_add_f32_e32 v169, v169, v45
	v_add_f32_e32 v168, v168, v46
	v_add_f32_e32 v169, v169, v47
	s_waitcnt lgkmcnt(4)
	v_mfma_f32_32x32x16_bf16 v[16:31], v[202:205], v[164:167], v[16:31]
	v_mfma_f32_32x32x16_bf16 v[0:15], v[206:209], v[164:167], v[0:15]
	v_exp_f32_e32 v48, v48
	v_exp_f32_e32 v49, v49
	v_exp_f32_e32 v50, v50
	v_exp_f32_e32 v51, v51
	v_exp_f32_e32 v52, v52
	v_exp_f32_e32 v53, v53
	v_exp_f32_e32 v54, v54
	v_exp_f32_e32 v55, v55
	v_cvt_pk_bf16_f32 v160, v48, v49
	v_cvt_pk_bf16_f32 v161, v50, v51
	v_cvt_pk_bf16_f32 v162, v52, v53
	v_cvt_pk_bf16_f32 v163, v54, v55
	v_add_f32_e32 v168, v168, v48
	v_add_f32_e32 v169, v169, v49
	v_add_f32_e32 v168, v168, v50
	v_add_f32_e32 v169, v169, v51
	v_add_f32_e32 v168, v168, v52
	v_add_f32_e32 v169, v169, v53
	v_add_f32_e32 v168, v168, v54
	v_add_f32_e32 v169, v169, v55
	s_waitcnt lgkmcnt(2)
	v_mfma_f32_32x32x16_bf16 v[16:31], v[210:213], v[160:163], v[16:31]
	v_mfma_f32_32x32x16_bf16 v[0:15], v[214:217], v[160:163], v[0:15]
	v_exp_f32_e32 v56, v56
	v_exp_f32_e32 v57, v57
	v_exp_f32_e32 v58, v58
	v_exp_f32_e32 v59, v59
	v_exp_f32_e32 v60, v60
	v_exp_f32_e32 v61, v61
	v_exp_f32_e32 v62, v62
	v_exp_f32_e32 v63, v63
	v_cvt_pk_bf16_f32 v164, v56, v57
	v_cvt_pk_bf16_f32 v165, v58, v59
	v_cvt_pk_bf16_f32 v166, v60, v61
	v_cvt_pk_bf16_f32 v167, v62, v63
	v_add_f32_e32 v168, v168, v56
	v_add_f32_e32 v169, v169, v57
	v_add_f32_e32 v168, v168, v58
	v_add_f32_e32 v169, v169, v59
	v_add_f32_e32 v168, v168, v60
	v_add_f32_e32 v169, v169, v61
	v_add_f32_e32 v168, v168, v62
	v_add_f32_e32 v169, v169, v63
	v_add_f32_e32 v168, v168, v169
	v_add_f32_e32 v119, v119, v168
	s_add_i32 s1, s1, 64
	s_cmpk_lg_i32 s1, 0x11c0
	s_waitcnt lgkmcnt(0)
	s_barrier
	v_mfma_f32_32x32x16_bf16 v[16:31], v[218:221], v[164:167], v[16:31]
	v_mfma_f32_32x32x16_bf16 v[0:15], v[222:225], v[164:167], v[0:15]
	s_cbranch_scc0 .LBB0_383
	s_mov_b32 s3, s2
	s_branch .LBB0_377

.Lsa_no_e0:
	s_waitcnt vmcnt(0)
	v_cmp_lt_i32_e32 vcc, v177, v176
	s_nop 1
	v_cndmask_b32_e32 v121, v175, v177, vcc
	v_lshlrev_b32_e32 v121, 2, v121
	s_setprio 1
	v_add_u32_e32 v88, v154, v155
	ds_read_b128 v[32:35], v88 offset:13312
	ds_read_b128 v[48:51], v88 offset:13344
	s_waitcnt lgkmcnt(1)
	v_mfma_f32_32x32x16_bf16 v[32:47], v[32:35], v[84:87], 0
	s_waitcnt lgkmcnt(0)
	v_mfma_f32_32x32x16_bf16 v[32:47], v[48:51], v[80:83], v[32:47]
	ds_read_b128 v[48:51], v88 offset:13376
	s_waitcnt lgkmcnt(0)
	v_mfma_f32_32x32x16_bf16 v[32:47], v[48:51], v[76:79], v[32:47]
	ds_read_b128 v[48:51], v88 offset:13408
	s_waitcnt lgkmcnt(0)
	v_mfma_f32_32x32x16_bf16 v[32:47], v[48:51], v[72:75], v[32:47]
	ds_read_b128 v[48:51], v88 offset:13440
	s_waitcnt lgkmcnt(0)
	v_mfma_f32_32x32x16_bf16 v[32:47], v[48:51], v[68:71], v[32:47]
	ds_read_b128 v[48:51], v88 offset:13472
	s_waitcnt lgkmcnt(0)
	v_mfma_f32_32x32x16_bf16 v[32:47], v[48:51], v[64:67], v[32:47]
	ds_read_b128 v[48:51], v88 offset:19968
	s_waitcnt lgkmcnt(0)
	v_mfma_f32_32x32x16_bf16 v[48:63], v[48:51], v[84:87], 0
	ds_read_b128 v[84:87], v88 offset:20000
	s_waitcnt lgkmcnt(0)
	v_mfma_f32_32x32x16_bf16 v[48:63], v[84:87], v[80:83], v[48:63]
	ds_read_b128 v[80:83], v88 offset:20032
	s_waitcnt lgkmcnt(0)
	v_mfma_f32_32x32x16_bf16 v[48:63], v[80:83], v[76:79], v[48:63]
	ds_read_b128 v[76:79], v88 offset:20064
	s_waitcnt lgkmcnt(0)
	v_mfma_f32_32x32x16_bf16 v[48:63], v[76:79], v[72:75], v[48:63]
	ds_read_b128 v[72:75], v88 offset:20096
	s_waitcnt lgkmcnt(0)
	v_mfma_f32_32x32x16_bf16 v[48:63], v[72:75], v[68:71], v[48:63]
	ds_read_b128 v[68:71], v88 offset:20128
	s_waitcnt lgkmcnt(0)
	v_mfma_f32_32x32x16_bf16 v[48:63], v[68:71], v[64:67], v[48:63]
	s_setprio 0
	s_nop 10
	v_max_f32_e32 v64, v48, v48
	v_max_f32_e32 v65, v32, v32
	v_max_f32_e32 v64, v65, v64
	v_max3_f32 v64, v64, v33, v49
	v_max3_f32 v64, v64, v34, v50
	v_max3_f32 v64, v64, v35, v51
	v_max3_f32 v64, v64, v36, v52
	v_max3_f32 v64, v64, v37, v53
	v_max3_f32 v64, v64, v38, v54
	v_max3_f32 v64, v64, v39, v55
	v_max3_f32 v64, v64, v40, v56
	v_max3_f32 v64, v64, v41, v57
	v_max3_f32 v64, v64, v42, v58
	v_max3_f32 v64, v64, v43, v59
	v_max3_f32 v64, v64, v44, v60
	v_max3_f32 v64, v64, v45, v61
	v_max3_f32 v64, v64, v46, v62
	v_max3_f32 v64, v64, v47, v63
	ds_bpermute_b32 v65, v121, v64
	s_waitcnt lgkmcnt(0)
	v_max_f32_e32 v65, v65, v65
	v_max_f32_e32 v64, v64, v65
	v_add_f32_e32 v65, 0x41000000, v151
	v_cmp_gt_f32_e32 vcc, v64, v65
	s_cbranch_vccz .LBB0_351
	v_max_f32_e32 v64, v64, v64
	v_max_f32_e32 v65, v151, v151
	v_max_f32_e32 v65, v65, v64
	v_sub_f32_e32 v64, v151, v65
	v_exp_f32_e32 v64, v64
	v_mov_b32_e32 v151, v65
	v_pk_mul_f32 v[30:31], v[30:31], v[64:65] op_sel_hi:[1,0]
	v_pk_mul_f32 v[28:29], v[28:29], v[64:65] op_sel_hi:[1,0]
	v_pk_mul_f32 v[26:27], v[26:27], v[64:65] op_sel_hi:[1,0]
	v_pk_mul_f32 v[24:25], v[24:25], v[64:65] op_sel_hi:[1,0]
	v_pk_mul_f32 v[22:23], v[22:23], v[64:65] op_sel_hi:[1,0]
	v_pk_mul_f32 v[20:21], v[20:21], v[64:65] op_sel_hi:[1,0]
	v_pk_mul_f32 v[18:19], v[18:19], v[64:65] op_sel_hi:[1,0]
	v_pk_mul_f32 v[16:17], v[16:17], v[64:65] op_sel_hi:[1,0]
	v_pk_mul_f32 v[14:15], v[14:15], v[64:65] op_sel_hi:[1,0]
	v_pk_mul_f32 v[12:13], v[12:13], v[64:65] op_sel_hi:[1,0]
	v_pk_mul_f32 v[10:11], v[10:11], v[64:65] op_sel_hi:[1,0]
	v_pk_mul_f32 v[8:9], v[8:9], v[64:65] op_sel_hi:[1,0]
	v_pk_mul_f32 v[6:7], v[6:7], v[64:65] op_sel_hi:[1,0]
	v_pk_mul_f32 v[4:5], v[4:5], v[64:65] op_sel_hi:[1,0]
	v_pk_mul_f32 v[2:3], v[2:3], v[64:65] op_sel_hi:[1,0]
	v_pk_mul_f32 v[0:1], v[0:1], v[64:65] op_sel_hi:[1,0]
	v_mul_f32_e32 v119, v119, v64
	s_branch .LBB0_351
